# speedup vs baseline: 1.0210x; 1.0068x over previous
; template <int DUMMY>
; __device__ void ssd_item(const Params& p, int item) {
;     ...
;     {
;       const int sfb = (wid & 1) * 2;
;       f32x4 cb[2];
;       cb[0] = f32x4{0.f, 0.f, 0.f, 0.f};
;       cb[1] = f32x4{0.f, 0.f, 0.f, 0.f};
; #pragma unroll
;       for (int ks = 0; ks < 4; ++ks) {
;         bf16x8 a = *(const bf16x8*)(Cs + (lf * 16 + fr) * 136 + ks * 32 + g4 * 8);
; #pragma unroll
;         for (int j = 0; j < 2; ++j) {
;           bf16x8 bb = *(const bf16x8*)(Bs + ((sfb + j) * 16 + fr) * 136 + ks * 32 + g4 * 8);
;           cb[j] = __builtin_amdgcn_mfma_f32_16x16x32_bf16(a, bb, cb[j], 0, 0, 0);
;         }
;       }
; #pragma unroll
;       for (int j = 0; j < 2; ++j) {
;         int s_ = (sfb + j) * 16 + fr;
;         float cs_s = cs[s_];
; #pragma unroll
;         for (int r = 0; r < 4; ++r) {
;           int l_ = lf * 16 + g4 * 4 + r;
;           float gv = (s_ <= l_) ? cb[j][r] * __expf(cs[l_] - cs_s) : 0.f;
;           Gs[l_ * 72 + s_] = f2bf(gv);
;         }
;       }
;     }
;     {
;       float dec = __expf(cs[63]);
; #pragma unroll
;       for (int j = 0; j < 2; ++j) {
;         accS[j][0] *= dec; accS[j][1] *= dec; accS[j][2] *= dec; accS[j][3] *= dec;
;       }
; #pragma unroll
;       for (int ks = 0; ks < 2; ++ks) {
;         bf16x8 a = *(const bf16x8*)(xwT + (pf * 16 + fr) * 72 + ks * 32 + g4 * 8);
; #pragma unroll
;         for (int j = 0; j < 2; ++j) {
;           bf16x8 bb = *(const bf16x8*)(BTs + ((nf0 + j) * 16 + fr) * 72 + ks * 32 + g4 * 8);
;           accS[j] = __builtin_amdgcn_mfma_f32_16x16x32_bf16(a, bb, accS[j], 0, 0, 0);
;         }
;       }
;     }
;     __builtin_amdgcn_s_setprio(0);
.LBB0_1051:
	s_or_b64 exec, exec, s[30:31]
	s_setprio 1
	v_add3_u32 v42, s3, v158, v161
	ds_read_b128 v[32:35], v42
	ds_read_b128 v[36:39], v154 offset:17408
	ds_read_b128 v[178:181], v154 offset:21760
	ds_read_b128 v[182:185], v42 offset:64
	ds_read_b128 v[186:189], v154 offset:17472
	ds_read_b128 v[220:223], v154 offset:21824
	ds_read_b128 v[224:227], v42 offset:128
	ds_read_b128 v[228:231], v154 offset:17536
	v_lshl_add_u32 v100, v121, 2, s52
	v_mov_b32_e32 v177, 0
	v_lshl_add_u32 v87, v119, 2, s52
	s_waitcnt lgkmcnt(6)
	v_mfma_f32_16x16x32_bf16 v[36:39], v[32:35], v[36:39], 0
	s_waitcnt lgkmcnt(5)
	v_mfma_f32_16x16x32_bf16 v[32:35], v[32:35], v[178:181], 0
	ds_read_b128 v[232:235], v154 offset:21888
	ds_read_b128 v[236:239], v42 offset:192
	ds_read_b128 v[240:243], v154 offset:17600
	ds_read_b128 v[244:247], v154 offset:21952
	ds_read_b32 v216, v87
	ds_read_b32 v217, v87 offset:4
	ds_read_b32 v218, v87 offset:8
	ds_read_b32 v219, v87 offset:12
	ds_read_b32 v101, v100
	ds_read_b32 v252, v100 offset:64
	s_waitcnt lgkmcnt(13)
	v_mfma_f32_16x16x32_bf16 v[36:39], v[182:185], v[186:189], v[36:39]
	s_waitcnt lgkmcnt(12)
	v_mfma_f32_16x16x32_bf16 v[32:35], v[182:185], v[220:223], v[32:35]
	s_waitcnt lgkmcnt(10)
	v_mfma_f32_16x16x32_bf16 v[36:39], v[224:227], v[228:231], v[36:39]
	s_waitcnt lgkmcnt(9)
	v_mfma_f32_16x16x32_bf16 v[32:35], v[224:227], v[232:235], v[32:35]
	s_waitcnt lgkmcnt(7)
	v_mfma_f32_16x16x32_bf16 v[36:39], v[236:239], v[240:243], v[36:39]
	s_waitcnt lgkmcnt(6)
	v_mfma_f32_16x16x32_bf16 v[32:35], v[236:239], v[244:247], v[32:35]
	s_waitcnt lgkmcnt(0)
	v_mov_b32_e32 v228, v252
	v_sub_f32_e32 v220, v216, v101
	v_sub_f32_e32 v221, v217, v101
	v_sub_f32_e32 v222, v218, v101
	v_sub_f32_e32 v223, v219, v101
	v_sub_f32_e32 v224, v216, v228
	v_sub_f32_e32 v225, v217, v228
	v_sub_f32_e32 v226, v218, v228
	v_sub_f32_e32 v227, v219, v228
	v_mul_f32_e32 v220, 0x3fb8aa3b, v220
	v_mul_f32_e32 v221, 0x3fb8aa3b, v221
	v_mul_f32_e32 v222, 0x3fb8aa3b, v222
	v_mul_f32_e32 v223, 0x3fb8aa3b, v223
	v_mul_f32_e32 v224, 0x3fb8aa3b, v224
	v_mul_f32_e32 v225, 0x3fb8aa3b, v225
	v_mul_f32_e32 v226, 0x3fb8aa3b, v226
	v_mul_f32_e32 v227, 0x3fb8aa3b, v227
	v_exp_f32_e32 v220, v220
	v_exp_f32_e32 v221, v221
	v_exp_f32_e32 v222, v222
	v_exp_f32_e32 v223, v223
	v_exp_f32_e32 v224, v224
	v_exp_f32_e32 v225, v225
	v_exp_f32_e32 v226, v226
	v_exp_f32_e32 v227, v227
	v_mul_f32_e32 v220, v36, v220
	v_mul_f32_e32 v221, v37, v221
	v_mul_f32_e32 v222, v38, v222
	v_mul_f32_e32 v223, v39, v223
	v_mul_f32_e32 v224, v32, v224
	v_mul_f32_e32 v225, v33, v225
	v_mul_f32_e32 v226, v34, v226
	v_mul_f32_e32 v227, v35, v227
	v_cvt_pk_bf16_f32 v220, v220, s0
	v_cvt_pk_bf16_f32 v221, v221, s0
	v_cvt_pk_bf16_f32 v222, v222, s0
	v_cvt_pk_bf16_f32 v223, v223, s0
	v_cvt_pk_bf16_f32 v224, v224, s0
	v_cvt_pk_bf16_f32 v225, v225, s0
	v_cvt_pk_bf16_f32 v226, v226, s0
	v_cvt_pk_bf16_f32 v227, v227, s0
	v_cndmask_b32_e64 v220, 0, v220, s[6:7]
	v_cndmask_b32_e64 v221, 0, v221, s[8:9]
	v_cndmask_b32_e64 v222, 0, v222, s[10:11]
	v_cndmask_b32_e64 v223, 0, v223, s[12:13]
	v_cndmask_b32_e64 v224, 0, v224, s[14:15]
	v_cndmask_b32_e64 v225, 0, v225, s[16:17]
	v_cndmask_b32_e64 v226, 0, v226, s[18:19]
	v_cndmask_b32_e64 v227, 0, v227, s[20:21]
	ds_write_b16 v124, v220
	ds_write_b16 v125, v221
	ds_write_b16 v126, v222
	ds_write_b16 v127, v223
	ds_write_b16 v128, v224
	ds_write_b16 v129, v225
	ds_write_b16 v130, v226
	v_mov_b32_e32 v32, v227
	v_mov_b32_e32 v33, s52
	ds_read_b32 v100, v33 offset:252
	ds_write_b16 v131, v32
	ds_read_b128 v[32:35], v134 offset:57856
	s_waitcnt lgkmcnt(7)
	ds_read_b128 v[36:39], v136 offset:34816
	ds_read_b128 v[178:181], v138 offset:34816
	ds_read_b128 v[182:185], v134 offset:57920
	ds_read_b128 v[186:189], v136 offset:34880
	s_waitcnt lgkmcnt(6)
	v_mul_f32_e32 v100, 0x3fb8aa3b, v100
	v_exp_f32_e32 v100, v100
	s_nop 0
	v_pk_mul_f32 v[6:7], v[6:7], v[100:101] op_sel_hi:[1,0]
	v_pk_mul_f32 v[4:5], v[4:5], v[100:101] op_sel_hi:[1,0]
	v_pk_mul_f32 v[2:3], v[2:3], v[100:101] op_sel_hi:[1,0]
	v_pk_mul_f32 v[0:1], v[0:1], v[100:101] op_sel_hi:[1,0]
	s_waitcnt lgkmcnt(3)
	v_mfma_f32_16x16x32_bf16 v[4:7], v[32:35], v[36:39], v[4:7]
	ds_read_b128 v[36:39], v138 offset:34880
	s_waitcnt lgkmcnt(3)
	v_mfma_f32_16x16x32_bf16 v[0:3], v[32:35], v[178:181], v[0:3]
	s_waitcnt lgkmcnt(1)
	v_mfma_f32_16x16x32_bf16 v[4:7], v[182:185], v[186:189], v[4:7]
	s_waitcnt lgkmcnt(0)
	v_mfma_f32_16x16x32_bf16 v[0:3], v[182:185], v[36:39], v[0:3]
	s_setprio 0
	s_waitcnt lgkmcnt(0)
	s_barrier
; __device__ __forceinline__ float bf2f(u16 h) { return __uint_as_float(((unsigned)h) << 16); }
; __device__ __forceinline__ float siluf_(float v) { return v * __builtin_amdgcn_rcpf(1.f + __expf(-v)); }
; #define DPPF(v, ctrl) __builtin_bit_cast(float, __builtin_amdgcn_update_dpp(0, __builtin_bit_cast(int, (v)), (ctrl), 0xf, 0xf, true))
; __device__ __forceinline__ float row16_sum(float v) {
;   v += DPPF(v, 0xB1);
;   v += DPPF(v, 0x4E);
;   v += DPPF(v, 0x141);
;   v += DPPF(v, 0x140);
;   return v;
; template <int DUMMY>
; __device__ void ssd_item(const Params& p, int item) {
;     ...
;       __builtin_amdgcn_s_setprio(0);
;       bf16x4 xs4 = *(const bf16x4*)(xT + (pf * 16 + fr) * 72 + lf * 16 + g4 * 4);
; #pragma unroll
;       for (int r = 0; r < 4; ++r) {
;         int l_ = lf * 16 + g4 * 4 + r;
;         float y = yd[r] + __expf(cs[l_]) * yo[r] + Dh * bf2f((u16)xs4[r]);
;         y *= siluf_(bf2f(zcur[r]));
;         ytile[l_ * 36 + pf * 16 + fr] = f2bf(y);
;         float sq = row16_sum(y * y);
;         if (fr == 0) sqs[wid * 16 + g4 * 4 + r] = sq;
;       }
	s_setprio 1
	ds_read_b128 v[32:35], v42
	v_add3_u32 v100, s78, v162, v161
	ds_read_b128 v[36:39], v100
	ds_read_b128 v[178:181], v132
	ds_read_b128 v[182:185], v42 offset:64
	ds_read_b128 v[186:189], v100 offset:64
	v_add3_u32 v101, s53, v160, v161
	s_waitcnt lgkmcnt(3)
	v_mfma_f32_16x16x32_bf16 v[32:35], v[32:35], v[36:39], 0
	ds_read_b128 v[36:39], v101
	ds_read_b128 v[190:193], v132 offset:64
	ds_read_b128 v[194:197], v101 offset:64
	s_waitcnt lgkmcnt(2)
	v_mfma_f32_16x16x32_bf16 v[178:181], v[178:181], v[36:39], 0
	ds_read_b128 v[36:39], v42 offset:128
	ds_read_b128 v[198:201], v42 offset:192
	v_mfma_f32_16x16x32_bf16 v[32:35], v[182:185], v[186:189], v[32:35]
	ds_read_b128 v[182:185], v100 offset:128
	ds_read_b128 v[186:189], v100 offset:192
	s_waitcnt lgkmcnt(1)
	v_mfma_f32_16x16x32_bf16 v[32:35], v[36:39], v[182:185], v[32:35]
	s_waitcnt lgkmcnt(0)
	v_mfma_f32_16x16x32_bf16 v[36:39], v[198:201], v[186:189], v[32:35]
	v_mfma_f32_16x16x32_bf16 v[32:35], v[190:193], v[194:197], v[178:181]
	s_setprio 0
	v_add_u32_e32 v42, s77, v160
	v_add3_u32 v42, v42, v163, v164
	ds_read_b64 v[100:101], v42
	v_lshlrev_b32_e32 v220, 16, v167
	v_lshlrev_b32_e32 v221, 16, v166
	v_lshlrev_b32_e32 v222, 16, v165
	v_lshlrev_b32_e32 v223, 16, v75
	v_mul_f32_e32 v224, 0xbfb8aa3b, v220
	v_mul_f32_e32 v225, 0xbfb8aa3b, v221
	v_mul_f32_e32 v226, 0xbfb8aa3b, v222
	v_mul_f32_e32 v227, 0xbfb8aa3b, v223
	v_mul_f32_e32 v228, 0x3fb8aa3b, v216
	v_mul_f32_e32 v229, 0x3fb8aa3b, v217
	v_mul_f32_e32 v230, 0x3fb8aa3b, v218
	v_mul_f32_e32 v231, 0x3fb8aa3b, v219
	v_exp_f32_e32 v224, v224
	v_exp_f32_e32 v225, v225
	v_exp_f32_e32 v226, v226
	v_exp_f32_e32 v227, v227
	v_exp_f32_e32 v228, v228
	v_exp_f32_e32 v229, v229
	v_exp_f32_e32 v230, v230
	v_exp_f32_e32 v231, v231
	v_add_f32_e32 v224, 1.0, v224
	v_add_f32_e32 v225, 1.0, v225
	v_add_f32_e32 v226, 1.0, v226
	v_add_f32_e32 v227, 1.0, v227
	v_rcp_f32_e32 v224, v224
	v_rcp_f32_e32 v225, v225
	v_rcp_f32_e32 v226, v226
	v_rcp_f32_e32 v227, v227
	v_fma_f32 v32, v36, v228, v32
	v_fma_f32 v33, v37, v229, v33
	v_fma_f32 v34, v38, v230, v34
	v_fmac_f32_e32 v35, v39, v231
	s_waitcnt lgkmcnt(0)
	v_lshlrev_b32_e32 v232, 16, v100
	v_and_b32_e32 v233, 0xffff0000, v100
	v_lshlrev_b32_e32 v234, 16, v101
	v_and_b32_e32 v235, 0xffff0000, v101
	v_fmac_f32_e32 v32, v43, v232
	v_mul_f32_e32 v233, v43, v233
	v_mul_f32_e32 v234, v43, v234
	v_mul_f32_e32 v235, v43, v235
	v_add_f32_e32 v33, v233, v33
	v_add_f32_e32 v34, v234, v34
	v_add_f32_e32 v35, v235, v35
	v_mul_f32_e32 v224, v224, v220
	v_mul_f32_e32 v225, v225, v221
	v_mul_f32_e32 v226, v226, v222
	v_mul_f32_e32 v227, v227, v223
	v_mul_f32_e32 v32, v224, v32
	v_mul_f32_e32 v33, v225, v33
	v_mul_f32_e32 v34, v226, v34
	v_mul_f32_e32 v35, v227, v35
	v_cvt_pk_bf16_f32 v228, v32, s0
	v_cvt_pk_bf16_f32 v229, v33, s0
	v_cvt_pk_bf16_f32 v230, v34, s0
	v_cvt_pk_bf16_f32 v231, v35, s0
	ds_write_b16 v123, v228
	ds_write_b16 v123, v229 offset:72
	ds_write_b16 v123, v230 offset:144
	ds_write_b16 v123, v231 offset:216
	v_mul_f32_e32 v236, v32, v32
	v_mul_f32_e32 v237, v33, v33
	v_mul_f32_e32 v238, v34, v34
	v_mul_f32_e32 v239, v35, v35
	v_mov_b32_dpp v240, v236 quad_perm:[1,0,3,2] row_mask:0xf bank_mask:0xf bound_ctrl:1
	v_mov_b32_dpp v241, v237 quad_perm:[1,0,3,2] row_mask:0xf bank_mask:0xf bound_ctrl:1
	v_mov_b32_dpp v242, v238 quad_perm:[1,0,3,2] row_mask:0xf bank_mask:0xf bound_ctrl:1
	v_mov_b32_dpp v243, v239 quad_perm:[1,0,3,2] row_mask:0xf bank_mask:0xf bound_ctrl:1
	v_fmac_f32_e32 v240, v32, v32
	v_fmac_f32_e32 v241, v33, v33
	v_fmac_f32_e32 v242, v34, v34
	v_fmac_f32_e32 v243, v35, v35
	v_add_f32_dpp v236, v240, v240 quad_perm:[2,3,0,1] row_mask:0xf bank_mask:0xf bound_ctrl:1
	v_add_f32_dpp v237, v241, v241 quad_perm:[2,3,0,1] row_mask:0xf bank_mask:0xf bound_ctrl:1
	v_add_f32_dpp v238, v242, v242 quad_perm:[2,3,0,1] row_mask:0xf bank_mask:0xf bound_ctrl:1
	v_add_f32_dpp v239, v243, v243 quad_perm:[2,3,0,1] row_mask:0xf bank_mask:0xf bound_ctrl:1
	v_add_f32_dpp v236, v236, v236 row_half_mirror row_mask:0xf bank_mask:0xf bound_ctrl:1
	v_add_f32_dpp v237, v237, v237 row_half_mirror row_mask:0xf bank_mask:0xf bound_ctrl:1
	v_add_f32_dpp v238, v238, v238 row_half_mirror row_mask:0xf bank_mask:0xf bound_ctrl:1
	v_add_f32_dpp v239, v239, v239 row_half_mirror row_mask:0xf bank_mask:0xf bound_ctrl:1
	v_mov_b32_dpp v240, v236 row_mirror row_mask:0xf bank_mask:0xf bound_ctrl:1
	v_mov_b32_dpp v241, v237 row_mirror row_mask:0xf bank_mask:0xf bound_ctrl:1
	v_mov_b32_dpp v242, v238 row_mirror row_mask:0xf bank_mask:0xf bound_ctrl:1
	v_mov_b32_dpp v243, v239 row_mirror row_mask:0xf bank_mask:0xf bound_ctrl:1
	s_and_saveexec_b64 s[30:31], s[0:1]
	v_add_f32_e32 v236, v236, v240
	v_add_f32_e32 v237, v237, v241
	v_add_f32_e32 v238, v238, v242
	v_add_f32_e32 v239, v239, v243
	ds_write_b32 v122, v236
	ds_write_b32 v122, v237 offset:4
	ds_write_b32 v122, v238 offset:8
	ds_write_b32 v122, v239 offset:12
	s_or_b64 exec, exec, s[30:31]
	s_add_u32 s70, s70, 0x40000
	s_addc_u32 s71, s71, 0
	s_mov_b64 s[30:31], 0x4000
	s_add_i32 s76, s76, 1
	s_waitcnt vmcnt(4)
	v_perm_b32 v42, v40, v176, s94
	v_perm_b32 v100, v176, v175, s94
	v_perm_b32 v101, v175, v173, s94
	v_perm_b32 v173, v173, v174, s94
	v_perm_b32 v171, v172, v171, s94
	v_lshl_add_u64 v[84:85], v[84:85], 0, s[60:61]
	v_add_u32_e32 v86, 64, v86
	v_lshl_add_u64 v[92:93], v[92:93], 0, s[30:31]
	v_lshl_add_u64 v[94:95], v[94:95], 0, s[62:63]
	v_lshl_add_u64 v[96:97], v[96:97], 0, s[62:63]
	s_cmp_eq_u32 s70, 0x1f00000
	v_lshl_add_u64 v[98:99], v[98:99], 0, s[60:61]
	s_waitcnt vmcnt(0)
	v_mov_b32_e32 v118, v255
	s_cbranch_scc1 .LBB0_1077
; template <int DUMMY>
; __device__ void ssd_item(const Params& p, int item) {
;     ...
;     for (int r = 0; r < 4; ++r) zcur[r] = znext[r];
;     if (c > 1) {
;       const size_t yi = (tb + (c - 2) * 64 + (tid >> 3)) * 4096 + h * 64 + ph * 32 + (tid & 7) * 4;
;       *(i32x2*)(zyo + (yi & omask)) = ypend;
;     }
;     if (c + 1 < 128) {
;       load_raw(c + 1);
;       const size_t zn = zbase + (size_t)64 * 4096;
; #pragma unroll
;       for (int r = 0; r < 4; ++r) znext[r] = zy[zn + (size_t)r * 4096];
	s_waitcnt vmcnt(0)
	v_mov_b32_e32 v75, v49
	v_mov_b32_e32 v165, v168
	v_mov_b32_e32 v166, v169
	v_mov_b32_e32 v167, v170
	v_lshl_add_u64 v[224:225], v[78:79], 0, s[70:71]
	v_lshl_add_u64 v[226:227], v[80:81], 0, s[70:71]
	v_add_co_u32_e32 v224, vcc, 0x100000, v224
	s_nop 1
	v_addc_co_u32_e32 v225, vcc, 0, v225, vcc
	v_add_co_u32_e32 v226, vcc, 0x100000, v226
	s_nop 1
	v_addc_co_u32_e32 v227, vcc, 0, v227, vcc
	global_load_dword v228, v[224:225], off
	global_load_dword v228, v[224:225], off offset:2048
	global_load_dword v228, v[226:227], off
	global_load_dword v228, v[226:227], off offset:2048
	v_add_u32_e32 v224, 61, v86
	v_mov_b32_e32 v225, v41
	v_lshl_add_u64 v[224:225], s[64:65], 0, v[224:225]
	v_mad_u64_u32 v[226:227], s[72:73], v224, s86, v[66:67]
	v_mad_i32_i24 v227, v225, s86, v227
	global_load_ushort v228, v[226:227], off
	v_add_co_u32_e32 v226, vcc, 0x3000, v226
	s_nop 1
	v_addc_co_u32_e32 v227, vcc, 0, v227, vcc
	global_load_ushort v228, v[226:227], off
	v_add_co_u32_e32 v226, vcc, 0x3000, v226
	s_nop 1
	v_addc_co_u32_e32 v227, vcc, 0, v227, vcc
	global_load_ushort v228, v[226:227], off
	v_add_co_u32_e32 v226, vcc, 0x3000, v226
	s_nop 1
	v_addc_co_u32_e32 v227, vcc, 0, v227, vcc
	global_load_ushort v228, v[226:227], off
	v_lshl_add_u64 v[224:225], v[84:85], 0, s[60:61]
	v_lshl_add_u64 v[224:225], s[42:43], 0, v[224:225]
	v_add_co_u32_e32 v226, vcc, 0xb280000, v224
	s_nop 1
	v_addc_co_u32_e32 v227, vcc, 0, v225, vcc
	global_load_ushort v228, v[226:227], off
	v_add_co_u32_e32 v226, vcc, 0xb282000, v224
	s_nop 1
	v_addc_co_u32_e32 v227, vcc, 0, v225, vcc
	global_load_ushort v228, v[226:227], off
	v_add_co_u32_e32 v226, vcc, 0xb284000, v224
	s_nop 1
	v_addc_co_u32_e32 v227, vcc, 0, v225, vcc
	global_load_ushort v228, v[226:227], off
	v_add_co_u32_e32 v226, vcc, 0xb286000, v224
	s_nop 1
	v_addc_co_u32_e32 v227, vcc, 0, v225, vcc
	global_load_ushort v228, v[226:227], off
	s_branch .LBB0_1033
